# MLP1 phase: per-row-panel-group start stagger (3 us steps) to interleave epilogue store bursts with other groups' K-loops
# baseline (speedup 1.0000x reference)
; #define LAS __attribute__((address_space(3)))
; #define PG8_STAGE(bufoff, gbase, voff) do { _Pragma("unroll") for (int _i = 0; _i < 2; ++_i) \
;         __builtin_amdgcn_global_load_lds((const unsigned*)((const char*)(gbase) + (voff)[_i]), (LAS unsigned*)(lds + (bufoff) + ldsw + _i * 8192), 16, 0, 0); } while (0)
; #define PG8_WAIT_V(n) asm volatile("s_waitcnt vmcnt(" #n ")" ::: "memory")
; #define PG8_BAR __builtin_amdgcn_s_barrier()
; template <class Epi, class Sched, bool ALIGN_EPI = false, bool SP2 = false>
; __device__ __forceinline__ void gemm_phase(LAS unsigned char* lds, const Gemm g, const Sched& S, const Epi& E) {
;     ...
;     const char* cA = (const char*)g.A + (size_t)cur.pm * tstep; const char* cB = (const char*)g.Bt + (size_t)cur.pn * tstep;
;     S.a_ready(cur);
;     if constexpr (SP2) {
;         PG8_STAGE(PG8_SB(0, 0), cB, voffB); PG8_STAGE(PG8_SB(0, 1), cB + hstep, voffB); PG8_STAGE(PG8_SA(0, 0), cA, voffA); PG8_STAGE(PG8_SA(0, 1), cA + hstep, voffA);
;         if (wr == 1) PG8_BAR;
;         PG8_WAIT_V(2); PG8_BAR;
;         PG8_STAGE(PG8_SB(1, 0), cB + kstep, voffB); PG8_STAGE(PG8_SA(1, 0), cA + kstep, voffA); PG8_STAGE(PG8_SB(1, 1), cB + hstep + kstep, voffB);
; __global__ void __launch_bounds__(512, 2) fwd_megakernel(Params p) {
;     ...
;         gemm_call<pg8::EpiH>(ldsl, XB, (const bf16_t*)(ws + WS_W1) + (size_t)l * FF * D, FF, D, pg8::EpiH{HID, SSQ, (LAS float*)(ldsl + 131072 + 1024), -1});
.LBB0_521:
	s_or_b64 exec, exec, s[24:25]
	v_readlane_b32 s4, v246, 56
	v_readlane_b32 s5, v246, 57
	s_lshl_b64 s[24:25], s[4:5], 23
	v_readlane_b32 s4, v246, 2
	v_mov_b32_e32 v5, v206
	v_readlane_b32 s5, v246, 3
	s_waitcnt lgkmcnt(0)
	s_barrier
	s_bfe_u32 s100, s2, 0x30003
	s_cmp_eq_u32 s100, 0
	s_cbranch_scc1 .Lstg_done_3
.Lstg_loop_3:
	s_sleep 100
	s_sub_u32 s100, s100, 1
	s_cmp_lg_u32 s100, 0
	s_cbranch_scc1 .Lstg_loop_3
.Lstg_done_3:
	s_andn2_b64 vcc, exec, s[4:5]
	v_readfirstlane_b32 s13, v5
	s_cbranch_vccnz .LBB0_547
	v_lshlrev_b32_e32 v0, 4, v5
	v_add_u32_e32 v1, 0x2000, v0
	v_ashrrev_i32_e32 v2, 31, v1
	v_lshrrev_b32_e32 v2, 22, v2
	v_add_u32_e32 v2, v1, v2
	v_ashrrev_i32_e32 v4, 10, v2
	v_mul_i32_i24_e32 v2, 0x400, v4
	v_sub_u32_e32 v1, v1, v2
	v_lshrrev_b32_e32 v2, 4, v1
	v_bitop3_b32 v1, v2, v1, 32 bitop3:0x6c
	v_ashrrev_i32_e32 v2, 31, v1
	v_lshrrev_b32_e32 v2, 26, v2
	v_add_u32_e32 v2, v1, v2
	v_lshlrev_b32_e32 v3, 3, v4
	v_ashrrev_i32_e32 v6, 6, v2
	v_and_b32_e32 v3, -16, v3
	v_add_u32_e32 v3, v6, v3
	v_and_b32_e32 v7, 3, v6
	s_mov_b32 s7, 0x1fffe0
	v_lshrrev_b32_e32 v8, 2, v3
	v_lshlrev_b32_e32 v9, 1, v3
	v_and_b32_e32 v2, 0xc0, v2
	v_and_or_b32 v7, v3, s7, v7
	v_and_b32_e32 v8, 4, v8
	v_and_b32_e32 v9, 24, v9
	v_sub_u32_e32 v1, v1, v2
	v_or3_b32 v8, v7, v8, v9
	v_lshlrev_b32_e32 v7, 5, v4
	v_ashrrev_i16_sdwa v1, v207, sext(v1) dst_sel:DWORD dst_unused:UNUSED_PAD src0_sel:DWORD src1_sel:BYTE_0
	v_and_b32_e32 v9, 32, v7
	v_bfe_i32 v7, v1, 0, 16
	v_add_lshl_u32 v1, v9, v7, 1
	v_lshl_add_u32 v162, v8, 11, v1
	v_lshl_add_u32 v164, v3, 11, v1
	v_bfe_i32 v1, v5, 27, 1
	v_lshrrev_b32_e32 v1, 22, v1
	v_add_u32_e32 v1, v0, v1
	v_and_b32_e32 v1, 0xfffffc00, v1
	v_sub_u32_e32 v0, v0, v1
	v_lshrrev_b32_e32 v1, 4, v0
	v_ashrrev_i32_e32 v2, 31, v5
	v_bitop3_b32 v0, v1, v0, 32 bitop3:0x6c
	v_lshrrev_b32_e32 v2, 26, v2
	v_ashrrev_i32_e32 v1, 31, v0
	v_add_u32_e32 v2, v5, v2
	v_lshrrev_b32_e32 v1, 26, v1
	v_ashrrev_i32_e32 v9, 6, v2
	v_add_u32_e32 v1, v0, v1
	v_lshlrev_b32_e32 v2, 3, v9
	v_ashrrev_i32_e32 v8, 6, v1
	v_and_b32_e32 v2, -16, v2
	v_readlane_b32 s4, v246, 0
	v_add_u32_e32 v2, v8, v2
	s_add_u32 s4, s4, s24
	v_readlane_b32 s5, v246, 1
	v_and_b32_e32 v3, 3, v8
	v_lshrrev_b32_e32 v10, 2, v2
	v_lshlrev_b32_e32 v11, 1, v2
	v_and_b32_e32 v1, 0xc0, v1
	s_addc_u32 s5, s5, s25
	s_ashr_i32 s36, s13, 6
	v_and_or_b32 v3, v2, s7, v3
	v_and_b32_e32 v10, 4, v10
	v_and_b32_e32 v11, 24, v11
	v_sub_u32_e32 v0, v0, v1
	s_ashr_i32 s28, s13, 8
	s_lshl_b32 s6, s36, 10
	v_or3_b32 v3, v3, v10, v11
	v_lshlrev_b32_e32 v10, 5, v9
	v_ashrrev_i16_sdwa v0, v207, sext(v0) dst_sel:DWORD dst_unused:UNUSED_PAD src0_sel:DWORD src1_sel:BYTE_0
	v_readlane_b32 s8, v246, 7
	v_and_b32_e32 v11, 32, v10
	v_bfe_i32 v10, v0, 0, 16
	v_readlane_b32 s9, v246, 8
	s_add_u32 s50, s4, s8
	v_add_lshl_u32 v0, v11, v10, 1
	s_addc_u32 s51, s5, s9
	s_add_i32 s7, s6, 0
	v_lshl_add_u32 v166, v3, 11, v0
	s_add_i32 m0, s7, 0x10000
	v_readlane_b32 s10, v246, 12
	global_load_lds_dwordx4 v166, s[50:51]
	s_add_i32 m0, s7, 0x12000
	s_add_u32 s8, s50, 0x40000
	global_load_lds_dwordx4 v162, s[50:51]
	s_addc_u32 s9, s51, 0
	s_add_i32 m0, s7, 0x14000
	v_lshl_add_u32 v168, v2, 11, v0
	global_load_lds_dwordx4 v166, s[8:9]
	s_add_i32 m0, s7, 0x16000
	v_readlane_b32 s11, v246, 13
	global_load_lds_dwordx4 v162, s[8:9]
	s_mov_b32 m0, s7
	s_add_i32 s8, s7, 0x2000
	s_add_i32 s9, s7, 0x4000
	s_nop 0
	global_load_lds_dwordx4 v168, s[10:11]
	s_mov_b32 m0, s8
	v_readlane_b32 s14, v246, 14
	global_load_lds_dwordx4 v164, s[10:11]
	s_mov_b32 m0, s9
	v_readlane_b32 s15, v246, 15
	s_add_i32 s10, s7, 0x6000
	v_mov_b32_e32 v167, v153
	v_mov_b32_e32 v163, v153
	s_cmp_eq_u32 s28, 1
	v_lshl_add_u64 v[0:1], s[50:51], 0, v[166:167]
	global_load_lds_dwordx4 v168, s[14:15]
	s_mov_b32 m0, s10
	s_cselect_b64 s[26:27], -1, 0
	global_load_lds_dwordx4 v164, s[14:15]
	s_cmp_lg_u32 s28, 1
	v_lshl_add_u64 v[2:3], s[50:51], 0, v[162:163]
	s_cbranch_scc1 .LBB0_524
	s_barrier
